# GEMM unit loop: accumulators zeroed with 64-bit moves; grid size kept in an SGPR for the phase instead of an s_load + wait per unit
# speedup vs baseline: 1.0194x; 1.0018x over previous
; __device__ __forceinline__ int bidx() { int t = blockIdx.x; asm volatile("" : "+s"(t)); return t; }
; __global__ void __launch_bounds__(512, 2) hymba_fwd(Params p) {
;     ...
;                 S.ntot = g.K / 64; S.G = (int)gridDim.x; S.c = bidx();
;                 pg8::gemm_phase(lds, g, S, E);
.LBB0_799:
	s_lshl_b32 s31, 64, s22
	s_lshl_b32 s34, s8, s71
	s_load_dword s32, s[0:1], 0xe8
	s_waitcnt lgkmcnt(0)
	s_mov_b32 s98, s32
	s_cmp_lg_u32 s32, s31
	s_cselect_b32 s32, 0, s32
	s_cmp_ge_u32 s26, s34
	s_cselect_b32 s32, 0, s32
	s_add_i32 s26, s26, s32
	s_sub_i32 s3, s26, s31
	s_sub_i32 s2, s3, s34
	s_cmp_ge_i32 s26, s31
	s_cselect_b64 s[6:7], -1, 0
	s_cmp_lt_i32 s3, s34
	s_cselect_b64 s[10:11], -1, 0
	s_cmp_ge_i32 s3, s34
	s_cselect_b64 s[4:5], -1, 0
	s_ashr_i32 s13, s3, s71
	s_mov_b64 s[8:9], -1
	s_and_b64 vcc, exec, s[6:7]
	s_cbranch_vccz .LBB0_801
	s_lshr_b32 s3, s13, s22
	s_add_i32 s3, s3, 64
	s_and_b64 s[8:9], s[10:11], exec
	s_cselect_b32 s36, s3, s2
	s_mov_b64 s[8:9], 0

; template <class Epi, class Sched>
; __device__ __forceinline__ void gemm_phase(LAS unsigned char* lds, const Gemm g, const Sched& S, const Epi& E) {
;     ...
;         const bool has_next = S.next(ui + 1, nxt);
;         const char* nA = has_next ? (const char*)g.A + (size_t)nxt.pm * tstep + (size_t)(nxt.k0 < 0 ? -1 - nxt.k0 : nxt.k0) * kstep : cA; const char* nB = has_next ? (const char*)g.Bt + (size_t)nxt.pn * tstep + (size_t)(nxt.k0 < 0 ? -1 - nxt.k0 : nxt.k0) * kstep : cB;
.LBB0_815:
	s_mov_b32 s10, s98
	s_add_i32 s45, s45, 1
	s_mov_b64 s[40:41], -1
	s_waitcnt lgkmcnt(0)
	s_mul_i32 s62, s45, s10
	s_add_i32 s62, s62, s26
	s_add_i32 s62, s62, s32
	s_cmp_eq_u32 s45, 1
	s_cselect_b32 s2, s26, s62
	s_cmp_lg_u32 s32, 0
	s_cselect_b32 s62, s2, s62
	s_sub_i32 s2, s62, s31
	s_sub_i32 s64, s2, s34
	s_cmp_ge_i32 s62, s31
	s_cselect_b64 s[12:13], -1, 0
	s_cmp_lt_i32 s2, s34
	s_cselect_b64 s[10:11], -1, 0
	s_ashr_i32 s63, s2, s23
	s_and_b64 vcc, exec, s[12:13]
	s_cbranch_vccz .LBB0_817
	s_lshr_b32 s2, s63, s22
	s_add_i32 s2, s2, 64
	s_and_b64 s[40:41], s[10:11], exec
	s_cselect_b32 s2, s2, s64
	s_mov_b64 s[40:41], 0

; template <class Epi, class Sched>
; __device__ __forceinline__ void gemm_phase(LAS unsigned char* lds, const Gemm g, const Sched& S, const Epi& E) {
;     ...
;         E(acc, cur, wr, wc, fr, fq); S.done(cur);
;         if (!has_next) break;
; #pragma unroll
;         for (int a = 0; a < 2; ++a)
; #pragma unroll
;             for (int b = 0; b < 2; ++b)
; #pragma unroll
;                 for (int m = 0; m < 4; ++m)
; #pragma unroll
;                     for (int n = 0; n < 2; ++n) acc[a][b][m][n] = (f32x4){0.f, 0.f, 0.f, 0.f};
;         cur = nxt; cA = nA; cB = nB; ++ui;
.LBB0_828:
	s_xor_b64 s[4:5], s[4:5], -1
	s_add_i32 s40, s77, -2
	s_add_u32 s6, s6, 0x80
	s_addc_u32 s7, s7, 0
	s_add_u32 s41, s8, 0x100
	s_addc_u32 vcc_lo, s9, 0
	s_mov_b32 s8, 0
	v_mov_b64_e32 v[0:1], 0
	v_mov_b64_e32 v[2:3], 0
	v_mov_b64_e32 v[4:5], 0
	v_mov_b64_e32 v[6:7], 0
	v_mov_b64_e32 v[8:9], 0
	v_mov_b64_e32 v[10:11], 0
	v_mov_b64_e32 v[12:13], 0
	v_mov_b64_e32 v[14:15], 0
	v_mov_b64_e32 v[18:19], 0
	v_mov_b64_e32 v[20:21], 0
	v_mov_b64_e32 v[22:23], 0
	v_mov_b64_e32 v[24:25], 0
	v_mov_b64_e32 v[26:27], 0
	v_mov_b64_e32 v[28:29], 0
	v_mov_b64_e32 v[30:31], 0
	v_mov_b64_e32 v[32:33], 0
	v_mov_b64_e32 v[34:35], 0
	v_mov_b64_e32 v[36:37], 0
	v_mov_b64_e32 v[38:39], 0
	v_mov_b64_e32 v[40:41], 0
	v_mov_b64_e32 v[42:43], 0
	v_mov_b64_e32 v[44:45], 0
	v_mov_b64_e32 v[46:47], 0
	v_mov_b64_e32 v[48:49], 0
	v_mov_b64_e32 v[50:51], 0
	v_mov_b64_e32 v[52:53], 0
	v_mov_b64_e32 v[54:55], 0
	v_mov_b64_e32 v[56:57], 0
	v_mov_b64_e32 v[58:59], 0
	v_mov_b64_e32 v[60:61], 0
	v_mov_b64_e32 v[62:63], 0
	v_mov_b64_e32 v[64:65], 0
	v_mov_b64_e32 v[66:67], 0
	v_mov_b64_e32 v[68:69], 0
	v_mov_b64_e32 v[70:71], 0
	v_mov_b64_e32 v[72:73], 0
	v_mov_b64_e32 v[74:75], 0
	v_mov_b64_e32 v[76:77], 0
	v_mov_b64_e32 v[78:79], 0
	v_mov_b64_e32 v[80:81], 0
	v_mov_b64_e32 v[82:83], 0
	v_mov_b64_e32 v[84:85], 0
	v_mov_b64_e32 v[86:87], 0
	v_mov_b64_e32 v[88:89], 0
	v_mov_b64_e32 v[90:91], 0
	v_mov_b64_e32 v[92:93], 0
	v_mov_b64_e32 v[94:95], 0
	v_mov_b64_e32 v[96:97], 0
	v_mov_b64_e32 v[98:99], 0
	v_mov_b64_e32 v[100:101], 0
	v_mov_b64_e32 v[102:103], 0
	v_mov_b64_e32 v[104:105], 0
	v_mov_b64_e32 v[106:107], 0
	v_mov_b64_e32 v[108:109], 0
	v_mov_b64_e32 v[110:111], 0
	v_mov_b64_e32 v[112:113], 0
	v_mov_b64_e32 v[114:115], 0
	v_mov_b64_e32 v[116:117], 0
	v_mov_b64_e32 v[118:119], 0
	v_mov_b64_e32 v[120:121], 0
	v_mov_b64_e32 v[122:123], 0
	v_mov_b64_e32 v[124:125], 0
	v_mov_b64_e32 v[126:127], 0
	v_mov_b64_e32 v[128:129], 0
	v_add_u32_e32 v16, 0x10000, v159
	ds_read_b128 v[144:147], v16
	ds_read_b128 v[148:151], v16 offset:1024
	ds_read_b128 v[152:155], v16 offset:2048
	ds_read_b128 v[162:165], v16 offset:3072

;     __device__ __forceinline__ void operator()(const f32x4 (&acc)[2][2][4][2], const Unit& u, int wr, int wc, int fr, int fq) const {
;         if (mode == 2) {
;             float* C = (float*)out;
;             const int row0 = u.pm * BM + wr * 64 + fr, col0 = u.pn * BM + wc * 32 + 4 * fq;
; #pragma unroll
;             for (int ai = 0; ai < 2; ++ai)
; #pragma unroll
;                 for (int m = 0; m < 4; ++m) { float* rowp = C + (size_t)(row0 + ai * HALF + m * 16) * ldc + col0;
; #pragma unroll
;                     for (int bj = 0; bj < 2; ++bj)
; #pragma unroll
;                         for (int n = 0; n < 2; ++n) { float* q = rowp + bj * HALF + n * 16; const f32x4 v = acc[ai][bj][m][n];
;                             if (u.k0 < 0) *(f32x4*)(scr + (size_t)u.sl * TS * DM + (q - C) - (size_t)64 * BM * ldc) = v;
;                             else *(f32x4*)q = *(f32x4*)q + v; } }
.LBB0_864:
	s_and_b64 vcc, exec, s[6:7]
	s_cbranch_vccz .LBB0_814
	v_or_b32_e32 v16, s3, v160
	v_lshl_add_u64 v[146:147], v[16:17], 2, s[52:53]
	v_lshl_add_u64 v[148:149], v[144:145], 2, v[146:147]
	s_mov_b64 s[6:7], -1
	s_and_b64 vcc, exec, s[4:5]
	s_cbranch_vccz .LBB0_867
	s_mov_b64 s[6:7], 0x10000
	s_mov_b64 s[40:41], 0x80000
	v_lshl_add_u64 v[150:151], v[148:149], 0, s[6:7]
	v_lshl_add_u64 v[162:163], v[148:149], 0, s[40:41]
	v_lshl_add_u64 v[152:153], v[150:151], 0, s[6:7]
	v_lshl_add_u64 v[164:165], v[162:163], 0, s[6:7]
	v_lshl_add_u64 v[154:155], v[152:153], 0, s[6:7]
	v_lshl_add_u64 v[198:199], v[164:165], 0, s[6:7]
	v_lshl_add_u64 v[200:201], v[198:199], 0, s[6:7]
	s_mov_b64 s[100:101], 0
	s_cmp_lg_u32 s27, 5
	s_cbranch_scc1 .Lepi_nodelta
	s_load_dwordx2 s[4:5], s[0:1], 0x0
	s_load_dwordx2 s[100:101], s[0:1], 0xd8
	s_waitcnt lgkmcnt(0)
	s_sub_u32 s100, s4, s100
	s_subb_u32 s101, s5, s101
